# retention chains assigned statically: workgroup bx < 64 takes chain bx (8 chains per XCD) instead of the first 64 arrivals at the work queue; no queue atomic on the chain start
# speedup vs baseline: 1.0034x; 1.0034x over previous
; __device__ __forceinline__ void ret_chain(ldsp lds, const bf16* proj, bf16* st, const float* ldr, int item, int tid) {
;     const int lane = tid & 63, w = __builtin_amdgcn_readfirstlane(tid >> 6), fr = lane & 15, fq = lane >> 4;
;     const int h = item & 7, b = (item >> 3) & 3, dir = item >> 5;
;     const float l2 = -__expf(ldr[dir * NRH + h]) * LOG2E, cd = __builtin_amdgcn_exp2f(l2 * (float)CHUNK);
;     const float a0 = dir ? 0.f : 127.f, a1 = dir ? 1.f : -1.f;
;     const int n0 = dir ? NCH - 1 : 0, step = dir ? -1 : 1;
;     const bf16* src = proj + (size_t)b * SEQ * INW + h * HDIM;
;     bf16* stp = st + (((size_t)dir * BATCH + b) * NRH + h) * (size_t)NCH * (HDIM * HDIM) + (size_t)((16 * w + (fq >> 1)) * 16 + fr) * 8 + 4 * (fq & 1);
;     TileRegs rvA, rkA, rvB, rkB;
;     tile_fetch(rvA, src + (size_t)n0 * CHUNK * INW + C_RV, INW, tid); tile_fetch(rkA, src + (size_t)n0 * CHUNK * INW + C_RK, INW, tid);
;     tile_fetch(rvB, src + (size_t)(n0 + step) * CHUNK * INW + C_RV, INW, tid); tile_fetch(rkB, src + (size_t)(n0 + step) * CHUNK * INW + C_RK, INW, tid);
.LBB0_296:
	s_or_b64 exec, exec, s[0:1]
	v_mov_b32_e32 v0, s46
	s_waitcnt lgkmcnt(0)
	s_barrier
	ds_read_b32 v0, v0
	s_mov_b32 s94, s63
	s_mov_b32 s83, s62
	s_mov_b64 s[90:91], s[60:61]
	v_readlane_b32 s60, v253, 11
	v_readlane_b32 s0, v255, 15
	v_readlane_b32 s68, v253, 19
	v_readlane_b32 s69, v253, 20
	s_lshl_b32 s78, s0, 4
	v_readlane_b32 s70, v253, 21
	v_readlane_b32 s71, v253, 22
	v_readlane_b32 s72, v253, 23
	v_readlane_b32 s73, v253, 24
	v_readlane_b32 s74, v253, 25
	v_readlane_b32 s75, v253, 26
	s_mov_b64 s[12:13], s[68:69]
	s_lshl_b64 s[8:9], s[78:79], 2
	s_mov_b64 s[14:15], s[70:71]
	s_mov_b64 s[18:19], s[74:75]
	v_readlane_b32 s61, v253, 12
	v_readlane_b32 s62, v253, 13
	v_readlane_b32 s63, v253, 14
	s_add_u32 s14, s18, s8
	s_waitcnt lgkmcnt(0)
	v_readfirstlane_b32 s12, v0
	v_cmp_lt_i32_e32 vcc, 63, v0
	v_add_u32_e32 v0, 0x200, v246
	v_add_u32_e32 v1, 0x400, v246
	v_add_u32_e32 v2, 0x600, v246
	v_lshlrev_b32_e32 v3, 4, v246
	s_mov_b64 s[16:17], s[72:73]
	s_addc_u32 s15, s19, s9
	v_readlane_b32 s12, v253, 0
	s_nop 1
	s_cmp_lt_u32 s12, 64
	s_cselect_b32 s12, s12, 64
	s_cselect_b64 vcc, 0, -1
	s_and_b64 vcc, exec, vcc
	v_ashrrev_i32_e32 v124, 4, v246
	v_ashrrev_i32_e32 v127, 4, v0
	v_ashrrev_i32_e32 v126, 4, v1
	v_ashrrev_i32_e32 v125, 4, v2
	v_and_b32_e32 v110, 0xf0, v3
	s_mov_b64 s[60:61], s[90:91]
	s_mov_b32 s62, s83
	s_mov_b32 s63, s94
	v_readlane_b32 s74, v255, 8
	s_movk_i32 s73, 0x1000
	s_mov_b32 s78, 0xf800000
	v_readlane_b32 s1, v255, 16
	v_readlane_b32 s64, v253, 15
	v_readlane_b32 s65, v253, 16
	v_readlane_b32 s66, v253, 17
	v_readlane_b32 s67, v253, 18
	s_cbranch_vccnz .LBB0_313
	v_and_b32_e32 v0, 15, v246
	v_lshrrev_b32_e32 v1, 1, v246
	v_cvt_f32_i32_e32 v226, v124
	v_cvt_f32_i32_e32 v133, v127
	v_cvt_f32_i32_e32 v134, v126
	v_cvt_f32_i32_e32 v135, v125
	v_bfe_u32 v12, v246, 2, 2
	v_and_or_b32 v111, v1, 16, v0
	v_lshrrev_b32_e32 v0, 2, v246
	v_lshlrev_b32_e32 v3, 3, v246
	s_movk_i32 s4, 0x2400
	v_and_or_b32 v1, v1, 24, v12
	v_and_b32_e32 v0, 4, v0
	v_and_b32_e32 v2, 0x78, v3
	v_mad_i64_i32 v[4:5], s[0:1], v124, s4, 0
	v_mad_i64_i32 v[6:7], s[0:1], v127, s4, 0
	v_mad_i64_i32 v[8:9], s[0:1], v126, s4, 0
	v_mad_i64_i32 v[10:11], s[0:1], v125, s4, 0
	v_mul_u32_u24_e32 v1, 0x110, v1
	v_and_b32_e32 v3, 24, v3
	v_add_u32_e32 v128, 0, v110
	v_mul_lo_u32 v129, v124, s47
	v_mul_lo_u32 v130, v127, s47
	v_mul_lo_u32 v131, v126, s47
	v_mul_lo_u32 v132, v125, s47
	v_add3_u32 v136, 0, v1, v3
	v_add_u32_e32 v137, s33, v110
	v_add_u32_e32 v138, s96, v110
	v_add3_u32 v139, s33, v1, v3
	v_add3_u32 v140, s96, v1, v3
	v_lshlrev_b32_e32 v98, 1, v0
	v_lshlrev_b32_e32 v16, 1, v2
	v_lshlrev_b64 v[100:101], 1, v[4:5]
	v_lshlrev_b64 v[102:103], 1, v[6:7]
	v_lshlrev_b64 v[104:105], 1, v[8:9]
	v_lshlrev_b64 v[106:107], 1, v[10:11]
	s_branch .LBB0_299
.LBB0_298:
	s_or_b64 exec, exec, s[0:1]
	v_mov_b32_e32 v0, s46
	s_waitcnt lgkmcnt(0)
	s_barrier
	ds_read_b32 v0, v0
	s_waitcnt lgkmcnt(0)
	v_cmp_gt_i32_e32 vcc, 64, v0
	v_readfirstlane_b32 s12, v0
	s_branch .LBB0_313
.LBB0_299:
	v_mov_b32_e32 v141, 0
	s_and_saveexec_b64 s[0:1], s[6:7]
	s_branch .LBB0_303
	s_mov_b64 s[10:11], exec
	v_mbcnt_lo_u32_b32 v0, s10, 0
	v_mbcnt_hi_u32_b32 v0, s11, v0
	v_cmp_eq_u32_e32 vcc, 0, v0
	s_and_saveexec_b64 s[4:5], vcc
	s_cbranch_execz .LBB0_302
	s_bcnt1_i32_b64 s10, s[10:11]
	v_mov_b32_e32 v1, s10
	global_atomic_add v1, v17, v1, s[20:21] sc0
